# speedup vs baseline: 1.1304x; 1.0038x over previous
; DEV int tidx() { int t = threadIdx.x; asm volatile("" : "+v"(t)); return t; }
; DEV unsigned xb_add(unsigned* p, unsigned v) { return __hip_atomic_fetch_add(p, v, __ATOMIC_RELAXED, __HIP_MEMORY_SCOPE_AGENT); }
; DEV void xbar(unsigned* bar, const unsigned* shinfo) {
;   asm volatile("s_waitcnt vmcnt(0)" ::: "memory");
;   __syncthreads();
;   if (tidx() == 0) {
;     const unsigned x = shinfo[0], nloc = shinfo[1], nx = shinfo[2];
;     __builtin_amdgcn_s_waitcnt(0);
;     const unsigned old = xb_add(&bar[XB_XSUB(x)], 1u);
.LBB0_154:
	s_or_b64 exec, exec, s[2:3]
	s_mov_b64 s[2:3], s[62:63]
	s_waitcnt vmcnt(0)
	v_mov_b32_e32 v0, v157
	s_waitcnt vmcnt(63) expcnt(7) lgkmcnt(15)
	s_barrier
	s_nop 0
	v_cmp_eq_u32_e32 vcc, 0, v0
	s_and_saveexec_b64 s[0:1], vcc
	s_cbranch_execz .Lxb0_204
	ds_read_b96 v[2:4], v200
	s_mov_b64 s[4:5], exec
	v_mbcnt_lo_u32_b32 v0, s4, 0
	s_add_u32 s22, s2, 0x2720100
	v_mbcnt_hi_u32_b32 v0, s5, v0
	s_waitcnt lgkmcnt(0)
	v_readfirstlane_b32 s6, v2
	s_addc_u32 s23, s3, 0
	s_lshl_b32 s24, s6, 6
	v_cmp_eq_u32_e32 vcc, 0, v0
	s_waitcnt vmcnt(0) expcnt(0) lgkmcnt(0)
	s_and_saveexec_b64 s[6:7], vcc
	s_cbranch_execz .Lxb0_170
	s_mov_b32 s9, s93
	s_add_i32 s8, s24, 0x500
	s_lshl_b64 s[8:9], s[8:9], 2
	s_add_u32 s8, s22, s8
	s_addc_u32 s9, s23, s9
	s_bcnt1_i32_b64 s4, s[4:5]
	v_mov_b32_e32 v2, s4
	global_atomic_add v2, v1, v2, s[8:9] sc0

; DEV int bidx() { int b = __builtin_amdgcn_readfirstlane(blockIdx.x); asm volatile("" : "+s"(b)); return b; }
; DEV int gdim() { int g = __builtin_amdgcn_readfirstlane(gridDim.x); asm volatile("" : "+s"(g)); return g; }
; #define ws (wsp(p))
; template <int EPI, bool AF32>
; DEV void gemm_phase(const void* A, int lda, const u16* Bt, int ldb, int M, int N, int K, const Epi& ea, char* smem) {
;   const int ntm = M >> 7, ntn = N >> 7;
;   for (int tile = bidx(); tile < ntm * ntn; tile += gdim()) {
;     int m, n;
;     tile_mn(tile, ntm, ntn, m, n);
;     gemm_tile<EPI, AF32>(A, lda, Bt, ldb, K, m << 7, n << 7, ea, smem);
; __global__ void __launch_bounds__(256, 2) fwd_megakernel(Params p) {
;     ...
;       gemm_phase<EP_F32, false>(XB, 1024, (const u16*)(ws + W_IN) + (size_t)4096 * 1024, 1024, T_ALL, 768, 1024, ea, smem);
.Lxb0_204:
	s_or_b64 exec, exec, s[0:1]
	v_mov_b32_e32 v0, v157
	v_mov_b32_e32 v2, v157
	s_barrier
.LBB0_162:
	s_mov_b64 s[0:1], s[62:63]
	s_mov_b64 s[4:5], s[62:63]
	s_mov_b32 s8, s52
	s_cmpk_gt_i32 s8, 0x617
	s_cbranch_scc1 .LBB0_167
	s_add_u32 s0, s0, 0xeb00000
	s_addc_u32 s1, s1, 0
	s_add_u32 s2, s4, 0x800000
	s_addc_u32 s3, s5, 0
	s_add_u32 s4, s4, 0x800100
	s_addc_u32 s5, s5, 0
